# P3/P6 rstd table: loads issued at phase entry, reduction and LDS write after the first tile loads are in flight (one cold round trip instead of two)
# speedup vs baseline: 1.0048x; 1.0048x over previous
.LBB0_303:
	s_cmp_lt_i32 s60, 4
	s_cselect_b64 s[6:7], -1, 0
	s_and_b64 s[8:9], s[6:7], s[4:5]
	s_andn2_b64 vcc, exec, s[8:9]
	s_cbranch_vccnz .LBB0_332
	s_cmpk_gt_i32 s2, 0xeff
	s_cbranch_scc1 .LBB0_332
	v_mbcnt_hi_u32_b32 v64, -1, v228
	v_lshl_add_u32 v64, s71, 6, v64
	s_and_b32 s98, s2, 7
	s_lshr_b32 s99, s2, 3
	s_and_b32 s99, s99, 7
	s_mul_i32 s98, s98, 40
	s_add_u32 s98, s98, s99
	s_lshl_b32 s98, s98, 8
	s_add_u32 s100, s30, 0x2c00000
	s_addc_u32 s101, s31, 0
	v_add_u32_e32 v65, 0, v64
	v_lshrrev_b32_e32 v66, 8, v65
	v_lshlrev_b32_e32 v66, 11, v66
	v_and_b32_e32 v67, 0xff, v65
	v_add3_u32 v66, v66, v67, s98
	v_lshlrev_b32_e32 v66, 6, v66
	global_load_dwordx4 v[68:71], v66, s[100:101] offset:0
	global_load_dwordx4 v[72:75], v66, s[100:101] offset:16
	global_load_dwordx4 v[76:79], v66, s[100:101] offset:32
	global_load_dwordx4 v[80:83], v66, s[100:101] offset:48
	v_add_u32_e32 v85, 512, v64
	v_lshrrev_b32_e32 v86, 8, v85
	v_lshlrev_b32_e32 v86, 11, v86
	v_and_b32_e32 v87, 0xff, v85
	v_add3_u32 v86, v86, v87, s98
	v_lshlrev_b32_e32 v86, 6, v86
	global_load_dwordx4 v[88:91], v86, s[100:101] offset:0
	global_load_dwordx4 v[92:95], v86, s[100:101] offset:16
	global_load_dwordx4 v[96:99], v86, s[100:101] offset:32
	global_load_dwordx4 v[100:103], v86, s[100:101] offset:48
	s_cmp_lt_u32 s71, 4
	s_cbranch_scc0 .Lrs_skip_2c00000
	v_add_u32_e32 v105, 1024, v64
	v_lshrrev_b32_e32 v106, 8, v105
	v_lshlrev_b32_e32 v106, 11, v106
	v_and_b32_e32 v107, 0xff, v105
	v_add3_u32 v106, v106, v107, s98
	v_lshlrev_b32_e32 v106, 6, v106
	global_load_dwordx4 v[108:111], v106, s[100:101] offset:0
	global_load_dwordx4 v[112:115], v106, s[100:101] offset:16
	global_load_dwordx4 v[116:119], v106, s[100:101] offset:32
	global_load_dwordx4 v[120:123], v106, s[100:101] offset:48
.Lrs_skip_2c00000:
	s_cmp_lt_u32 s71, 4
	s_cselect_b32 s99, 1, 0
	s_add_u32 s70, s30, 0x1200000
	s_mov_b32 s4, s71
	v_mbcnt_hi_u32_b32 v9, -1, v228
	s_addc_u32 s71, s31, 0
	s_lshl_b32 s72, s4, 10
	v_lshlrev_b32_e32 v14, 4, v9
	v_add_u32_e32 v0, s72, v14
	s_waitcnt lgkmcnt(0)
	v_add_u32_e32 v1, 0x2000, v0
	v_ashrrev_i32_e32 v2, 31, v1
	v_lshrrev_b32_e32 v2, 22, v2
	v_add_u32_e32 v2, v1, v2
	v_ashrrev_i32_e32 v8, 10, v2
	v_mul_i32_i24_e32 v2, 0x400, v8
	v_sub_u32_e32 v1, v1, v2
	v_lshrrev_b32_e32 v2, 4, v1
	v_bitop3_b32 v1, v2, v1, 32 bitop3:0x6c
	v_ashrrev_i32_e32 v2, 31, v1
	v_lshrrev_b32_e32 v2, 26, v2
	v_add_u32_e32 v2, v1, v2
	v_ashrrev_i32_e32 v10, 6, v2
	v_lshlrev_b32_e32 v3, 3, v8
	v_and_b32_e32 v2, 0xffc0, v2
	v_and_b32_e32 v3, -16, v3
	v_sub_u32_e32 v1, v1, v2
	v_add_u32_e32 v3, v10, v3
	v_lshrrev_b16_e32 v2, 7, v1
	v_and_b32_e32 v4, 3, v10
	s_mov_b32 s4, 0x1fffe0
	v_lshrrev_b32_e32 v5, 2, v3
	v_lshlrev_b32_e32 v6, 1, v3
	v_and_b32_e32 v2, 1, v2
	v_and_or_b32 v4, v3, s4, v4
	v_and_b32_e32 v5, 4, v5
	v_and_b32_e32 v6, 24, v6
	v_add_u16_e32 v1, v1, v2
	v_mov_b32_e32 v2, 1
	v_or3_b32 v4, v4, v5, v6
	v_lshlrev_b32_e32 v5, 5, v8
	v_ashrrev_i16_sdwa v1, v2, sext(v1) dst_sel:DWORD dst_unused:UNUSED_PAD src0_sel:DWORD src1_sel:BYTE_0
	v_and_b32_e32 v5, 32, v5
	v_bfe_i32 v11, v1, 0, 16
	v_add_lshl_u32 v1, v5, v11, 1
	v_lshl_add_u32 v144, v4, 11, v1
	v_lshl_add_u32 v146, v3, 11, v1
	v_ashrrev_i32_e32 v1, 31, v0
	v_lshrrev_b32_e32 v1, 22, v1
	v_add_u32_e32 v1, v0, v1
	v_ashrrev_i32_e32 v12, 10, v1
	v_mul_i32_i24_e32 v1, 0x400, v12
	v_sub_u32_e32 v0, v0, v1
	v_lshrrev_b32_e32 v1, 4, v0
	v_bitop3_b32 v0, v1, v0, 32 bitop3:0x6c
	v_ashrrev_i32_e32 v1, 31, v0
	v_lshrrev_b32_e32 v1, 26, v1
	v_add_u32_e32 v1, v0, v1
	v_lshlrev_b32_e32 v3, 3, v12
	v_ashrrev_i32_e32 v13, 6, v1
	v_and_b32_e32 v3, -16, v3
	v_add_u32_e32 v3, v13, v3
	v_and_b32_e32 v4, 3, v13
	s_ashr_i32 s73, s2, 31
	v_and_or_b32 v4, v3, s4, v4
	s_lshr_b32 s4, s73, 29
	s_add_i32 s4, s2, s4
	s_ashr_i32 s6, s4, 3
	s_and_b32 s4, s4, -8
	s_lshr_b32 s5, s3, 8
	s_sub_i32 s4, s2, s4
	s_cmp_lt_i32 s4, 0
	s_movk_i32 s74, 0x1e1
	s_cselect_b32 s7, s74, 0x1e0
	s_mul_i32 s4, s4, s7
	s_add_i32 s4, s4, s6
	s_mul_hi_i32 s6, s4, 0x2aaaaaab
	s_lshr_b32 s7, s6, 31
	s_ashr_i32 s6, s6, 4
	s_add_i32 s6, s6, s7
	s_lshl_b32 s7, s6, 3
	s_mulk_i32 s6, 0x60
	s_sub_i32 s6, s4, s6
	s_bfe_i32 s4, s6, 0x80000
	s_bfe_u32 s4, s4, 0x3000c
	s_add_i32 s10, s6, s4
	s_bfe_i32 s4, s10, 0x80000
	s_and_b32 s10, s10, 0xf8
	s_sub_i32 s6, s6, s10
	s_sext_i32_i16 s4, s4
	s_sext_i32_i8 s6, s6
	v_lshrrev_b32_e32 v5, 2, v3
	v_lshlrev_b32_e32 v6, 1, v3
	v_and_b32_e32 v1, 0xc0, v1
	s_lshr_b32 s4, s4, 3
	s_add_i32 s50, s7, s6
	v_and_b32_e32 v5, 4, v5
	v_and_b32_e32 v6, 24, v6
	v_sub_u32_e32 v0, v0, v1
	s_ashr_i32 s51, s50, 31
	s_bfe_i64 s[10:11], s[4:5], 0x100000
	v_or3_b32 v4, v4, v5, v6
	v_lshlrev_b32_e32 v5, 5, v12
	v_ashrrev_i16_sdwa v0, v2, sext(v0) dst_sel:DWORD dst_unused:UNUSED_PAD src0_sel:DWORD src1_sel:BYTE_0
	s_lshl_b64 s[6:7], s[50:51], 19
	s_lshl_b64 s[10:11], s[10:11], 19
	v_and_b32_e32 v5, 32, v5
	v_bfe_i32 v15, v0, 0, 16
	s_add_u32 s54, s70, s10
	v_add_lshl_u32 v0, v5, v15, 1
	s_addc_u32 s55, s71, s11
	s_add_i32 s75, s72, 0
	v_lshl_add_u32 v148, v4, 11, v0
	s_add_i32 m0, s75, 0x10000
	v_lshl_add_u32 v150, v3, 11, v0
	global_load_lds_dwordx4 v148, s[54:55]
	s_add_i32 m0, s75, 0x12000
	s_add_u32 s10, s54, 0x40000
	global_load_lds_dwordx4 v144, s[54:55]
	s_addc_u32 s11, s55, 0
	s_add_i32 m0, s75, 0x14000
	v_mov_b32_e32 v153, 0
	global_load_lds_dwordx4 v148, s[10:11]
	s_add_i32 m0, s75, 0x16000
	s_add_u32 s52, s62, s6
	s_addc_u32 s53, s63, s7
	s_add_i32 s76, s75, 0x2000
	global_load_lds_dwordx4 v144, s[10:11]
	s_mov_b32 m0, s75
	s_add_u32 s6, s52, 0x40000
	global_load_lds_dwordx4 v150, s[52:53]
	s_mov_b32 m0, s76
	s_addc_u32 s7, s53, 0
	s_add_i32 s77, s75, 0x4000
	global_load_lds_dwordx4 v146, s[52:53]
	s_mov_b32 m0, s77
	s_add_i32 s78, s75, 0x6000
	global_load_lds_dwordx4 v150, s[6:7]
	s_mov_b32 m0, s78
	v_mov_b32_e32 v149, v153
	global_load_lds_dwordx4 v146, s[6:7]
	v_mov_b32_e32 v124, 0x358637bd
	s_waitcnt vmcnt(8)
	v_add_f32_e32 v68, v68, v69
	v_add_f32_e32 v70, v70, v71
	v_add_f32_e32 v68, v68, v70
	v_add_f32_e32 v72, v72, v73
	v_add_f32_e32 v74, v74, v75
	v_add_f32_e32 v72, v72, v74
	v_add_f32_e32 v76, v76, v77
	v_add_f32_e32 v78, v78, v79
	v_add_f32_e32 v76, v76, v78
	v_add_f32_e32 v80, v80, v81
	v_add_f32_e32 v82, v82, v83
	v_add_f32_e32 v80, v80, v82
	v_add_f32_e32 v68, v68, v72
	v_add_f32_e32 v76, v76, v80
	v_add_f32_e32 v68, v68, v76
	v_fmamk_f32 v68, v68, 0x3a800000, v124
	v_rsq_f32_e32 v68, v68
	v_lshlrev_b32_e32 v66, 2, v65
	v_add_u32_e32 v66, 0x20800, v66
	ds_write_b32 v66, v68
	v_add_f32_e32 v88, v88, v89
	v_add_f32_e32 v90, v90, v91
	v_add_f32_e32 v88, v88, v90
	v_add_f32_e32 v92, v92, v93
	v_add_f32_e32 v94, v94, v95
	v_add_f32_e32 v92, v92, v94
	v_add_f32_e32 v96, v96, v97
	v_add_f32_e32 v98, v98, v99
	v_add_f32_e32 v96, v96, v98
	v_add_f32_e32 v100, v100, v101
	v_add_f32_e32 v102, v102, v103
	v_add_f32_e32 v100, v100, v102
	v_add_f32_e32 v88, v88, v92
	v_add_f32_e32 v96, v96, v100
	v_add_f32_e32 v88, v88, v96
	v_fmamk_f32 v88, v88, 0x3a800000, v124
	v_rsq_f32_e32 v88, v88
	v_lshlrev_b32_e32 v86, 2, v85
	v_add_u32_e32 v86, 0x20800, v86
	ds_write_b32 v86, v88
	s_cmp_eq_u32 s99, 1
	s_cbranch_scc0 .Lrs_done_2c00000
	v_add_f32_e32 v108, v108, v109
	v_add_f32_e32 v110, v110, v111
	v_add_f32_e32 v108, v108, v110
	v_add_f32_e32 v112, v112, v113
	v_add_f32_e32 v114, v114, v115
	v_add_f32_e32 v112, v112, v114
	v_add_f32_e32 v116, v116, v117
	v_add_f32_e32 v118, v118, v119
	v_add_f32_e32 v116, v116, v118
	v_add_f32_e32 v120, v120, v121
	v_add_f32_e32 v122, v122, v123
	v_add_f32_e32 v120, v120, v122
	v_add_f32_e32 v108, v108, v112
	v_add_f32_e32 v116, v116, v120
	v_add_f32_e32 v108, v108, v116
	v_fmamk_f32 v108, v108, 0x3a800000, v124
	v_rsq_f32_e32 v108, v108
	v_lshlrev_b32_e32 v106, 2, v105
	v_add_u32_e32 v106, 0x20800, v106
	ds_write_b32 v106, v108
.Lrs_done_2c00000:
	s_waitcnt lgkmcnt(0)
	v_mov_b32_e32 v145, v153
	v_mov_b32_e32 v151, v153
	v_mov_b32_e32 v147, v153
	s_cmp_eq_u32 s5, 1
	v_writelane_b32 v254, s90, 11
	s_mov_b32 s11, 0
	v_lshl_add_u64 v[6:7], s[54:55], 0, v[148:149]
	v_lshl_add_u64 v[2:3], s[54:55], 0, v[144:145]
	v_lshl_add_u64 v[0:1], s[52:53], 0, v[150:151]
	s_cselect_b64 s[26:27], -1, 0
	s_cmp_lg_u32 s5, 1
	v_lshl_add_u64 v[4:5], s[52:53], 0, v[146:147]
	v_writelane_b32 v254, s91, 12
	s_cbranch_scc1 .LBB0_307
	s_barrier

.LBB0_747:
	s_cmp_lt_i32 s60, 7
	s_cselect_b64 s[6:7], -1, 0
	s_and_b64 s[8:9], s[6:7], s[4:5]
	s_andn2_b64 vcc, exec, s[8:9]
	s_cbranch_vccnz .LBB0_766
	s_cmpk_gt_i32 s2, 0x1b7f
	s_cbranch_scc1 .LBB0_766
	v_mbcnt_hi_u32_b32 v64, -1, v228
	v_lshl_add_u32 v64, s71, 6, v64
	s_and_b32 s98, s2, 7
	s_lshr_b32 s99, s2, 3
	s_and_b32 s99, s99, 7
	s_sub_u32 s99, 7, s99
	s_mul_i32 s98, s98, 40
	s_add_u32 s98, s98, s99
	s_lshl_b32 s98, s98, 8
	s_add_u32 s100, s30, 0x3200000
	s_addc_u32 s101, s31, 0
	v_add_u32_e32 v65, 0, v64
	v_lshrrev_b32_e32 v66, 8, v65
	v_lshlrev_b32_e32 v66, 11, v66
	v_and_b32_e32 v67, 0xff, v65
	v_add3_u32 v66, v66, v67, s98
	v_lshlrev_b32_e32 v66, 6, v66
	global_load_dwordx4 v[68:71], v66, s[100:101] offset:0
	global_load_dwordx4 v[72:75], v66, s[100:101] offset:16
	global_load_dwordx4 v[76:79], v66, s[100:101] offset:32
	global_load_dwordx4 v[80:83], v66, s[100:101] offset:48
	v_add_u32_e32 v85, 512, v64
	v_lshrrev_b32_e32 v86, 8, v85
	v_lshlrev_b32_e32 v86, 11, v86
	v_and_b32_e32 v87, 0xff, v85
	v_add3_u32 v86, v86, v87, s98
	v_lshlrev_b32_e32 v86, 6, v86
	global_load_dwordx4 v[88:91], v86, s[100:101] offset:0
	global_load_dwordx4 v[92:95], v86, s[100:101] offset:16
	global_load_dwordx4 v[96:99], v86, s[100:101] offset:32
	global_load_dwordx4 v[100:103], v86, s[100:101] offset:48
	s_cmp_lt_u32 s71, 4
	s_cbranch_scc0 .Lrs_skip_3200000
	v_add_u32_e32 v105, 1024, v64
	v_lshrrev_b32_e32 v106, 8, v105
	v_lshlrev_b32_e32 v106, 11, v106
	v_and_b32_e32 v107, 0xff, v105
	v_add3_u32 v106, v106, v107, s98
	v_lshlrev_b32_e32 v106, 6, v106
	global_load_dwordx4 v[108:111], v106, s[100:101] offset:0
	global_load_dwordx4 v[112:115], v106, s[100:101] offset:16
	global_load_dwordx4 v[116:119], v106, s[100:101] offset:32
	global_load_dwordx4 v[120:123], v106, s[100:101] offset:48
.Lrs_skip_3200000:
	s_cmp_lt_u32 s71, 4
	s_cselect_b32 s99, 1, 0
	s_add_u32 s40, s30, 0x1a00000
	s_addc_u32 s41, s31, 0
	v_mbcnt_hi_u32_b32 v9, -1, v228
	s_lshl_b32 s42, s71, 10
	v_lshl_add_u32 v0, v9, 4, s42
	s_waitcnt lgkmcnt(0)
	v_add_u32_e32 v1, 0x2000, v0
	v_ashrrev_i32_e32 v2, 31, v1
	v_lshrrev_b32_e32 v2, 22, v2
	v_add_u32_e32 v2, v1, v2
	v_ashrrev_i32_e32 v8, 10, v2
	v_mul_i32_i24_e32 v2, 0x400, v8
	v_sub_u32_e32 v1, v1, v2
	v_lshrrev_b32_e32 v2, 4, v1
	v_bitop3_b32 v1, v2, v1, 32 bitop3:0x6c
	v_ashrrev_i32_e32 v2, 31, v1
	v_lshrrev_b32_e32 v2, 26, v2
	v_add_u32_e32 v2, v1, v2
	v_ashrrev_i32_e32 v10, 6, v2
	v_lshlrev_b32_e32 v3, 3, v8
	v_and_b32_e32 v2, 0xffc0, v2
	v_and_b32_e32 v3, -16, v3
	v_sub_u32_e32 v1, v1, v2
	v_add_u32_e32 v3, v10, v3
	v_lshrrev_b16_e32 v2, 7, v1
	v_and_b32_e32 v4, 3, v10
	s_mov_b32 s4, 0x1fffe0
	v_lshrrev_b32_e32 v5, 2, v3
	v_lshlrev_b32_e32 v6, 1, v3
	v_and_b32_e32 v2, 1, v2
	v_and_or_b32 v4, v3, s4, v4
	v_and_b32_e32 v5, 4, v5
	v_and_b32_e32 v6, 24, v6
	v_add_u16_e32 v1, v1, v2
	v_mov_b32_e32 v2, 1
	v_or3_b32 v4, v4, v5, v6
	v_lshlrev_b32_e32 v5, 5, v8
	v_ashrrev_i16_sdwa v1, v2, sext(v1) dst_sel:DWORD dst_unused:UNUSED_PAD src0_sel:DWORD src1_sel:BYTE_0
	v_and_b32_e32 v5, 32, v5
	v_bfe_i32 v11, v1, 0, 16
	v_add_lshl_u32 v1, v5, v11, 1
	v_lshl_add_u32 v128, v4, 11, v1
	v_lshl_add_u32 v130, v3, 11, v1
	v_ashrrev_i32_e32 v1, 31, v0
	v_lshrrev_b32_e32 v1, 22, v1
	v_add_u32_e32 v1, v0, v1
	v_ashrrev_i32_e32 v12, 10, v1
	v_mul_i32_i24_e32 v1, 0x400, v12
	v_sub_u32_e32 v0, v0, v1
	v_lshrrev_b32_e32 v1, 4, v0
	v_bitop3_b32 v0, v1, v0, 32 bitop3:0x6c
	v_ashrrev_i32_e32 v1, 31, v0
	v_lshrrev_b32_e32 v1, 26, v1
	v_add_u32_e32 v1, v0, v1
	v_lshlrev_b32_e32 v3, 3, v12
	v_ashrrev_i32_e32 v13, 6, v1
	v_and_b32_e32 v3, -16, v3
	v_add_u32_e32 v3, v13, v3
	v_and_b32_e32 v4, 3, v13
	s_ashr_i32 s43, s2, 31
	v_and_or_b32 v4, v3, s4, v4
	s_lshr_b32 s4, s43, 29
	s_add_i32 s4, s2, s4
	s_ashr_i32 s6, s4, 3
	s_and_b32 s4, s4, -8
	s_lshr_b32 s5, s3, 8
	s_sub_i32 s4, s2, s4
	s_cmp_lt_i32 s4, 0
	s_movk_i32 s44, 0x371
	s_cselect_b32 s7, s44, 0x370
	s_mul_i32 s4, s4, s7
	s_add_i32 s4, s4, s6
	s_mul_hi_i32 s6, s4, 0x2e8ba2e9
	s_lshr_b32 s7, s6, 31
	s_ashr_i32 s6, s6, 5
	s_add_i32 s6, s6, s7
	s_mul_i32 s7, s6, 0xb0
	s_sub_i32 s7, s4, s7
	s_sext_i32_i16 s4, s7
	s_bfe_u32 s4, s4, 0x3001c
	s_add_i32 s12, s7, s4
	s_sext_i32_i16 s4, s12
	s_and_b32 s12, s12, 0xfff8
	s_sub_i32 s7, s7, s12
	s_lshl_b32 s6, s6, 3
	s_sext_i32_i16 s7, s7
	s_add_i32 s6, s6, s7
	s_mul_hi_i32 s7, s6, 0x66666667
	s_lshr_b32 s12, s7, 31
	s_ashr_i32 s7, s7, 4
	s_add_i32 s7, s7, s12
	s_mul_i32 s7, s7, 40
	s_sub_i32 s7, s6, s7
	s_lshl_b32 s7, s7, 1
	s_sub_i32 s6, s6, s7
	v_lshrrev_b32_e32 v5, 2, v3
	v_lshlrev_b32_e32 v6, 1, v3
	v_and_b32_e32 v1, 0xc0, v1
	s_lshr_b32 s4, s4, 3
	s_add_i32 s26, s6, 39
	v_and_b32_e32 v5, 4, v5
	v_and_b32_e32 v6, 24, v6
	v_sub_u32_e32 v0, v0, v1
	s_ashr_i32 s27, s26, 31
	s_bfe_i64 s[12:13], s[4:5], 0x100000
	v_or3_b32 v4, v4, v5, v6
	v_lshlrev_b32_e32 v5, 5, v12
	v_ashrrev_i16_sdwa v0, v2, sext(v0) dst_sel:DWORD dst_unused:UNUSED_PAD src0_sel:DWORD src1_sel:BYTE_0
	s_lshl_b64 s[6:7], s[26:27], 19
	s_lshl_b64 s[12:13], s[12:13], 19
	v_and_b32_e32 v5, 32, v5
	v_bfe_i32 v14, v0, 0, 16
	s_add_u32 s36, s40, s12
	v_add_lshl_u32 v0, v5, v14, 1
	s_addc_u32 s37, s41, s13
	s_add_i32 s27, s42, 0
	v_lshl_add_u32 v132, v4, 11, v0
	s_add_i32 m0, s27, 0x10000
	v_lshl_add_u32 v134, v3, 11, v0
	global_load_lds_dwordx4 v132, s[36:37]
	s_add_i32 m0, s27, 0x12000
	s_add_u32 s12, s36, 0x40000
	global_load_lds_dwordx4 v128, s[36:37]
	s_addc_u32 s13, s37, 0
	s_add_i32 m0, s27, 0x14000
	v_mov_b32_e32 v133, 0
	global_load_lds_dwordx4 v132, s[12:13]
	s_add_i32 m0, s27, 0x16000
	s_add_u32 s38, s62, s6
	s_addc_u32 s39, s63, s7
	s_add_i32 s45, s27, 0x2000
	global_load_lds_dwordx4 v128, s[12:13]
	s_mov_b32 m0, s27
	s_add_u32 s6, s38, 0x40000
	global_load_lds_dwordx4 v134, s[38:39]
	s_mov_b32 m0, s45
	s_addc_u32 s7, s39, 0
	s_add_i32 s46, s27, 0x4000
	global_load_lds_dwordx4 v130, s[38:39]
	s_mov_b32 m0, s46
	s_add_i32 s47, s27, 0x6000
	global_load_lds_dwordx4 v134, s[6:7]
	s_mov_b32 m0, s47
	v_mov_b32_e32 v129, v133
	global_load_lds_dwordx4 v130, s[6:7]
	v_mov_b32_e32 v124, 0x358637bd
	s_waitcnt vmcnt(8)
	v_add_f32_e32 v68, v68, v69
	v_add_f32_e32 v70, v70, v71
	v_add_f32_e32 v68, v68, v70
	v_add_f32_e32 v72, v72, v73
	v_add_f32_e32 v74, v74, v75
	v_add_f32_e32 v72, v72, v74
	v_add_f32_e32 v76, v76, v77
	v_add_f32_e32 v78, v78, v79
	v_add_f32_e32 v76, v76, v78
	v_add_f32_e32 v80, v80, v81
	v_add_f32_e32 v82, v82, v83
	v_add_f32_e32 v80, v80, v82
	v_add_f32_e32 v68, v68, v72
	v_add_f32_e32 v76, v76, v80
	v_add_f32_e32 v68, v68, v76
	v_fmamk_f32 v68, v68, 0x3a800000, v124
	v_rsq_f32_e32 v68, v68
	v_lshlrev_b32_e32 v66, 2, v65
	v_add_u32_e32 v66, 0x20800, v66
	ds_write_b32 v66, v68
	v_add_f32_e32 v88, v88, v89
	v_add_f32_e32 v90, v90, v91
	v_add_f32_e32 v88, v88, v90
	v_add_f32_e32 v92, v92, v93
	v_add_f32_e32 v94, v94, v95
	v_add_f32_e32 v92, v92, v94
	v_add_f32_e32 v96, v96, v97
	v_add_f32_e32 v98, v98, v99
	v_add_f32_e32 v96, v96, v98
	v_add_f32_e32 v100, v100, v101
	v_add_f32_e32 v102, v102, v103
	v_add_f32_e32 v100, v100, v102
	v_add_f32_e32 v88, v88, v92
	v_add_f32_e32 v96, v96, v100
	v_add_f32_e32 v88, v88, v96
	v_fmamk_f32 v88, v88, 0x3a800000, v124
	v_rsq_f32_e32 v88, v88
	v_lshlrev_b32_e32 v86, 2, v85
	v_add_u32_e32 v86, 0x20800, v86
	ds_write_b32 v86, v88
	s_cmp_eq_u32 s99, 1
	s_cbranch_scc0 .Lrs_done_3200000
	v_add_f32_e32 v108, v108, v109
	v_add_f32_e32 v110, v110, v111
	v_add_f32_e32 v108, v108, v110
	v_add_f32_e32 v112, v112, v113
	v_add_f32_e32 v114, v114, v115
	v_add_f32_e32 v112, v112, v114
	v_add_f32_e32 v116, v116, v117
	v_add_f32_e32 v118, v118, v119
	v_add_f32_e32 v116, v116, v118
	v_add_f32_e32 v120, v120, v121
	v_add_f32_e32 v122, v122, v123
	v_add_f32_e32 v120, v120, v122
	v_add_f32_e32 v108, v108, v112
	v_add_f32_e32 v116, v116, v120
	v_add_f32_e32 v108, v108, v116
	v_fmamk_f32 v108, v108, 0x3a800000, v124
	v_rsq_f32_e32 v108, v108
	v_lshlrev_b32_e32 v106, 2, v105
	v_add_u32_e32 v106, 0x20800, v106
	ds_write_b32 v106, v108
.Lrs_done_3200000:
	s_waitcnt lgkmcnt(0)
	v_mov_b32_e32 v135, v133
	v_mov_b32_e32 v131, v133
	s_cmp_eq_u32 s5, 1
	s_mov_b32 s48, 0
	v_lshl_add_u64 v[6:7], s[36:37], 0, v[132:133]
	v_lshl_add_u64 v[4:5], s[36:37], 0, v[128:129]
	v_lshl_add_u64 v[0:1], s[38:39], 0, v[134:135]
	s_cselect_b64 s[12:13], -1, 0
	s_cmp_lg_u32 s5, 1
	v_lshl_add_u64 v[2:3], s[38:39], 0, v[130:131]
	s_cbranch_scc1 .LBB0_751
	s_barrier
